# weights: late set (FFN2, xo) of layer w converted in layer w's own cross-attn step together with the early set of layer w+1; prologue keeps only K/V projections + early set of layer 0
# speedup vs baseline: 1.0282x; 1.0059x over previous
; #define LAS __attribute__((address_space(3)))
; #define TR_UP(IDX, GIDX, WT, ISUP) { const int kb = r / 88, n0 = (r % 88) * 32; transpose_item(P.in[IDX] + oU, D, DFF, P.in[GIDX] + l * D, WT, (n0 >> 7) * 256 + (n0 & 127) + (ISUP) * 128, scr, kb, n0, lane); return; }
; __device__ __forceinline__ void weight_item(const Params& P, unsigned char* ws, LAS float* scr, int l, int r, int lane) {
;     constexpr int I_UP = WI_UP, I_DN = WI_DN, I_IN = WI_IN, I_SQ = WI_SQ;
;         bf16_t* W1a = (bf16_t*)(ws + WS_W1) + (size_t)(2 * l) * 2 * DFF * D; bf16_t* W1b = W1a + (size_t)2 * DFF * D;
;         bf16_t* WDa = (bf16_t*)(ws + WS_WD) + (size_t)(2 * l) * D * DFF; bf16_t* WDb = WDa + (size_t)D * DFF;
;         const size_t oU = (size_t)l * D * DFF, oS = (size_t)l * D * D;
;     ...
;         if (r < I_UP) TR_UP(10, 9, W1a, 0)
;         r -= I_UP;
;         if (r < I_UP) TR_UP(11, 9, W1a, 1)
;         r -= I_UP;
;         if (r < I_UP) TR_UP(28, 27, W1b, 0)
;         r -= I_UP;
;         if (r < I_UP) TR_UP(29, 27, W1b, 1)
;         r -= I_UP;
;     ...
;         if (r < I_DN) { const int kb = r / 32, n0 = (r % 32) * 32; transpose_item(P.in[12] + oU, DFF, D, nullptr, WDa, n0, scr, kb, n0, lane); return; }
;         r -= I_DN;
;         if (r < I_DN) { const int kb = r / 32, n0 = (r % 32) * 32; transpose_item(P.in[30] + oU, DFF, D, nullptr, WDb, n0, scr, kb, n0, lane); return; }
;         r -= I_DN;
;         if (r < I_IN) { const int kb = r / 80, n0 = (r % 80) * 32; transpose_item(P.in[14] + (size_t)l * D * DIN, D, DIN, P.in[13] + l * D, (bf16_t*)(ws + WS_WIN) + (size_t)l * DIN * D, n0, scr, kb, n0, lane); return; }
;         r -= I_IN;
;         {
;             const int q = r / I_SQ; r %= I_SQ; const int kb = r / 32, n0 = (r % 32) * 32;
.LBB0_11:
	s_mul_hi_i32 s2, s48, 0x2aaaaaab
	s_lshr_b32 s3, s2, 31
	s_ashr_i32 s2, s2, 11
	s_add_i32 s18, s2, s3
	s_mul_i32 s2, s18, 0xffffd000
	s_add_i32 s51, s48, s2
	s_mov_b32 s98, 0
	s_cmp_ge_u32 s51, 0xb00
	s_addc_u32 s98, s98, 0
	s_cmp_ge_u32 s51, 0x1600
	s_addc_u32 s98, s98, 0
	s_cmp_ge_u32 s51, 0x1b80
	s_addc_u32 s98, s98, 0
	s_cmp_ge_u32 s51, 0x2100
	s_addc_u32 s98, s98, 0
	s_cmp_ge_u32 s51, 0x2a00
	s_addc_u32 s98, s98, 0
	s_cmp_ge_u32 s51, 0x2c00
	s_addc_u32 s98, s98, 0
	s_cmp_lg_u32 s32, 0
	s_cbranch_scc1 .Lwd_fdef
	s_cmp_lg_u32 s96, 0x100
	s_cbranch_scc1 .Lwd_take
	s_cmp_eq_u32 s98, 6
	s_cbranch_scc1 .Lwd_take
	s_cmp_lg_u32 s18, 0
	s_cbranch_scc1 .LBB0_10
	s_bitcmp1_b32 s98, 0
	s_cbranch_scc1 .LBB0_10
	s_branch .Lwd_take
.Lwd_fdef:
	s_sub_i32 s99, s18, s32
	s_add_i32 s99, s99, s98
	s_bitcmp1_b32 s99, 0
	s_cbranch_scc1 .LBB0_10

; __global__ void __launch_bounds__(512, 2) mega_fwd(Params P) {
;     ...
;         if (s == 2 || s == 5 || step == 0) {
;             pg8::Gemm g; pg8::StaticOrder S; pg8::EpiScale E; const float* ssp = SS;
;             if (step == 0) { ssp = (const float*)(ws + WS_SSM); g = pg8::Gemm{(const bf16_t*)(ws + WS_MEMB), (const bf16_t*)(ws + WS_WKV), 512, 8192, D}; S.init(512, 8192, G, (bxs + 64) % G);
;                 E = pg8::EpiScale{(bf16_t*)(ws + WS_MEMKV), 1024, 1.0f, 1, P.out + OFF_MK}; }
;             else if (s == 2) { g = pg8::Gemm{XB, (const bf16_t*)(ws + WS_WIN) + (size_t)l * DIN * D, T, DIN, D}; S.init(T, DIN, G, bxs);
;                 E = pg8::EpiScale{Z, DIN, 1.0f, 0, nullptr}; }
;             else { g = pg8::Gemm{XB, (const bf16_t*)(ws + WS_WXQ) + (size_t)l * D * D, TP, D, D}; S.init(TP, D, G, bxs);
;                 E = pg8::EpiScale{Q2, D, 0.0625f * LOG2E, 0, nullptr}; }
;             pg8::gemm_phase(lds, g, S, E, ssp);
.LBB0_278:
	v_readlane_b32 s0, v253, 0
	v_readlane_b32 s1, v254, 56
	s_cmp_lt_u32 s0, 0x80
	s_cbranch_scc1 .Lwd_skip
	s_cmp_lg_u32 s96, 0x100
	s_cbranch_scc1 .Lwd_skip
	s_mov_b32 s2, 0
	s_cmp_eq_u32 s1, 5
	s_cselect_b32 s2, 1, s2
	s_cmp_eq_u32 s1, 14
	s_cselect_b32 s2, 2, s2
	s_cmp_eq_u32 s1, 23
	s_cselect_b32 s2, 3, s2
	s_cmp_eq_u32 s1, 32
	s_cselect_b32 s2, 4, s2
	s_cmp_eq_u32 s2, 0
	s_cbranch_scc0 .Lwd_entry

; #define LAS __attribute__((address_space(3)))
; __device__ __forceinline__ void weights_deferred(const Params& P, LAS unsigned char* lds, int l, int part, int nparts) {
;     int tid = threadIdx.x; asm volatile("" : "+v"(tid));
;     const int lane = tid & 63, wave = __builtin_amdgcn_readfirstlane(tid >> 6);
;     LAS float* scr = (LAS float*)(lds + wave * 16384);
;     for (int r = part * NW + wave; r < W_NOKV; r += nparts * NW) weight_item(P, P.ws, scr, l, r, lane);
; }
; __device__ __forceinline__ void prologue(const Params& P, LAS unsigned char* lds, int G, int vcu) {
;     int tid = threadIdx.x; asm volatile("" : "+v"(tid));
;     const int lane = tid & 63, wave = __builtin_amdgcn_readfirstlane(tid >> 6);
;     LAS float* scr = (LAS float*)(lds + wave * 16384);
;     unsigned char* ws = P.ws;
;     const int gw = vcu * NW + wave, NGW = G * NW;
;     for (int it = gw; it < NL * W_PER_L; it += NGW) weight_item(P, ws, scr, it / W_PER_L, it % W_PER_L, lane);
.Lwd_entry:
	v_writelane_b32 v250, s0, 0
	v_writelane_b32 v250, s1, 1
	v_writelane_b32 v250, s2, 2
	v_writelane_b32 v250, s3, 3
	v_writelane_b32 v250, s4, 4
	v_writelane_b32 v250, s5, 5
	v_writelane_b32 v250, s6, 6
	v_writelane_b32 v250, s7, 7
	v_writelane_b32 v250, s8, 8
	v_writelane_b32 v250, s9, 9
	v_writelane_b32 v250, s10, 10
	v_writelane_b32 v250, s11, 11
	v_writelane_b32 v250, s12, 12
	v_writelane_b32 v250, s13, 13
	v_writelane_b32 v250, s14, 14
	v_writelane_b32 v250, s15, 15
	v_writelane_b32 v250, s16, 16
	v_writelane_b32 v250, s17, 17
	v_writelane_b32 v250, s18, 18
	v_writelane_b32 v250, s19, 19
	v_writelane_b32 v250, s20, 20
	v_writelane_b32 v250, s21, 21
	v_writelane_b32 v250, s22, 22
	v_writelane_b32 v250, s23, 23
	v_writelane_b32 v250, s24, 24
	v_writelane_b32 v250, s25, 25
	v_writelane_b32 v250, s26, 26
	v_writelane_b32 v250, s27, 27
	v_writelane_b32 v250, s28, 28
	v_writelane_b32 v250, s29, 29
	v_writelane_b32 v250, s30, 30
	v_writelane_b32 v250, s31, 31
	v_writelane_b32 v250, s32, 32
	v_writelane_b32 v250, s33, 33
	v_writelane_b32 v250, s34, 34
	v_writelane_b32 v250, s35, 35
	v_writelane_b32 v250, s36, 36
	v_writelane_b32 v250, s37, 37
	v_writelane_b32 v250, s38, 38
	v_writelane_b32 v250, s39, 39
	v_writelane_b32 v250, s40, 40
	v_writelane_b32 v250, s41, 41
	v_writelane_b32 v250, s42, 42
	v_writelane_b32 v250, s43, 43
	v_writelane_b32 v250, s44, 44
	v_writelane_b32 v250, s45, 45
	v_writelane_b32 v250, s46, 46
	v_writelane_b32 v250, s47, 47
	v_writelane_b32 v250, s48, 48
	v_writelane_b32 v250, s49, 49
	v_writelane_b32 v250, s50, 50
	v_writelane_b32 v250, s51, 51
	v_writelane_b32 v250, s52, 52
	v_writelane_b32 v250, s53, 53
	v_writelane_b32 v250, s54, 54
	v_writelane_b32 v250, s55, 55
	v_writelane_b32 v250, s56, 56
	v_writelane_b32 v250, s57, 57
	v_writelane_b32 v250, s58, 58
	v_writelane_b32 v250, s59, 59
	v_writelane_b32 v250, s60, 60
	v_writelane_b32 v250, s61, 61
	v_writelane_b32 v250, s62, 62
	v_writelane_b32 v250, s63, 63
	v_writelane_b32 v251, s64, 0
	v_writelane_b32 v251, s65, 1
	v_writelane_b32 v251, s66, 2
	v_writelane_b32 v251, s67, 3
	v_writelane_b32 v251, s68, 4
	v_writelane_b32 v251, s69, 5
	v_writelane_b32 v251, s70, 6
	v_writelane_b32 v251, s71, 7
	v_writelane_b32 v251, s72, 8
	v_writelane_b32 v251, s73, 9
	v_writelane_b32 v251, s74, 10
	v_writelane_b32 v251, s75, 11
	v_writelane_b32 v251, s76, 12
	v_writelane_b32 v251, s77, 13
	v_writelane_b32 v251, s78, 14
	v_writelane_b32 v251, s79, 15
	s_mov_b32 s32, s2
	s_add_i32 s3, s0, 0xffffff80
	s_mul_i32 s2, s2, 0x3000
	s_lshl_b32 s3, s3, 3
	s_add_i32 s61, s2, 0x29ff
	s_min_u32 s61, s61, 0xbfff
	s_add_i32 s2, s2, 0xffffdb00
	s_add_i32 s26, s2, s3
	v_readlane_b32 s0, v255, 60
	v_readlane_b32 s1, v255, 61
	v_mov_b32_e32 v1, v208
	s_movk_i32 s60, 0x400
	v_readfirstlane_b32 s2, v1
	v_and_b32_e32 v34, 63, v1
	s_ashr_i32 s27, s2, 6
	s_add_i32 s26, s26, s27
	s_lshl_b32 s2, s27, 14
	s_add_i32 s6, s2, 0
	s_add_u32 s28, s94, 0x18000000
	s_addc_u32 s29, s95, 0
	s_add_u32 s30, s94, 0x1d800000
	s_addc_u32 s31, s95, 0
	s_add_u32 s34, s94, 0x22800000
	s_addc_u32 s35, s95, 0
	s_add_u32 s36, s94, 0x22000000
	s_addc_u32 s37, s95, 0
	s_load_dwordx16 s[8:23], s[0:1], 0x80
	s_add_u32 s38, s94, 0x21800000
	s_addc_u32 s39, s95, 0
	v_and_b32_e32 v3, 7, v1
	s_add_u32 s40, s94, 0x20400000
	s_load_dwordx16 s[44:59], s[0:1], 0x40
	v_mov_b32_e32 v37, 0
	v_lshlrev_b32_e32 v36, 4, v3
	s_addc_u32 s41, s95, 0
	s_load_dwordx16 s[64:79], s[0:1], 0xc0
	v_lshrrev_b32_e32 v1, 3, v34
	v_lshl_add_u64 v[4:5], s[94:95], 0, v[36:37]
	s_mov_b64 s[2:3], 0x23000000
	s_waitcnt lgkmcnt(0)
	s_cmp_lg_u64 s[20:21], 0
	v_lshlrev_b32_e32 v2, 2, v3
	v_lshlrev_b32_e32 v38, 3, v3
	v_mul_u32_u24_e32 v3, 0x420, v3
	v_lshl_add_u64 v[40:41], v[4:5], 0, s[2:3]
	v_lshlrev_b32_e32 v4, 2, v1
	s_cselect_b64 s[2:3], -1, 0
	s_cmp_lg_u64 s[18:19], 0
	v_add_u32_e32 v35, s6, v36
	v_add3_u32 v53, s6, v3, v4
	s_cselect_b64 s[6:7], -1, 0
	s_cmp_lg_u64 s[14:15], 0
	s_cselect_b64 s[8:9], -1, 0
	s_cmp_lg_u64 s[54:55], 0
	s_cselect_b64 s[10:11], -1, 0
	s_cmp_lg_u64 s[70:71], 0
	s_cselect_b64 s[12:13], -1, 0
	s_cmp_lg_u64 s[46:47], 0
	v_mul_u32_u24_e32 v39, 0x84, v1
	v_or_b32_e32 v45, 8, v1
	v_or_b32_e32 v47, 16, v1
	v_or_b32_e32 v51, 24, v1
	v_cndmask_b32_e64 v55, 0, 1, s[2:3]
	v_lshlrev_b32_e32 v42, 2, v2
	v_mov_b32_e32 v57, 0x8000
	v_mov_b32_e32 v59, 0x10000
	v_mov_b32_e32 v60, 0x18000
	v_mov_b32_e32 v61, 0x20000
	v_mov_b32_e32 v62, 0x28000
	v_mov_b32_e32 v63, 0x30000
	v_mov_b32_e32 v64, 0x38000
	s_cselect_b64 s[14:15], -1, 0
	s_lshl_b32 s42, s26, 1
	s_lshl_b32 s43, s60, 1
	s_lshl_b32 s44, s26, 5
	s_lshl_b32 s45, s60, 5
	s_movk_i32 s46, 0x2800
	s_movk_i32 s47, 0x2c00
	s_mov_b32 s48, s26
	s_mov_b32 s17, 0
	s_branch .LBB0_11
